# GEMM phase prologues: first counted wait moved below the second batch of stage loads (vmcnt(4) -> vmcnt(10)), all 14 prologue LDS-DMA loads in one burst, 8 phases
# baseline (speedup 1.0000x reference)
.LBB0_173:
	s_and_b32 s3, s0, 3
	s_mov_b64 s[0:1], 0x80
	s_add_i32 m0, s58, 0x18000
	v_lshl_add_u64 v[6:7], v[6:7], 0, s[0:1]
	s_ashr_i32 s63, s90, 31
	s_ashr_i32 s64, s16, 31
	s_lshl_b32 s6, s2, 13
	s_lshl_b32 s7, s3, 12
	global_load_lds_dwordx4 v[6:7], off
	v_lshl_add_u64 v[4:5], v[4:5], 0, s[0:1]
	s_add_i32 m0, s58, 0x1a000
	s_add_i32 s65, s58, 0x8000
	s_add_i32 s66, s58, 0xa000
	global_load_lds_dwordx4 v[4:5], off
	v_lshl_add_u64 v[2:3], v[2:3], 0, s[0:1]
	s_mov_b32 m0, s65
	s_add_u32 s4, s52, 0x10080
	global_load_lds_dwordx4 v[2:3], off
	v_lshl_add_u64 v[0:1], v[0:1], 0, s[0:1]
	s_mov_b32 m0, s66
	s_addc_u32 s5, s53, 0
	global_load_lds_dwordx4 v[0:1], off
	s_add_i32 m0, s58, 0x1c000
	v_lshl_add_u64 v[0:1], s[4:5], 0, v[130:131]
	global_load_lds_dwordx4 v[0:1], off
	v_lshl_add_u64 v[0:1], s[4:5], 0, v[134:135]
	s_add_i32 m0, s58, 0x1e000
	v_lshlrev_b32_e32 v3, 2, v8
	global_load_lds_dwordx4 v[0:1], off
	v_bfe_u32 v1, v8, 4, 2
	v_and_b32_e32 v0, 15, v8
	v_lshlrev_b32_e32 v2, 4, v1
	v_lshl_or_b32 v2, v0, 6, v2
	v_and_b32_e32 v3, 32, v3
	v_bitop3_b32 v4, v2, s6, v3 bitop3:0xde
	v_bitop3_b32 v158, v2, s7, v3 bitop3:0xde
	v_cmp_gt_u32_e64 s[6:7], 8, v0
	v_lshl_or_b32 v139, s2, 6, v0
	s_lshl_b32 s87, s3, 6
	v_cndmask_b32_e64 v0, 32, 0, s[6:7]
	v_lshl_or_b32 v138, v1, 3, v0
	v_lshlrev_b32_e32 v0, 14, v9
	v_and_b32_e32 v0, 0xffff8000, v0
	v_cmp_gt_u32_e64 s[2:3], 2, v1
	v_cmp_eq_u32_e64 s[4:5], 0, v1
	v_lshl_add_u32 v0, v10, 11, v0
	v_and_b32_e32 v1, 1, v9
	v_lshl_or_b32 v0, v1, 6, v0
	v_lshl_add_u32 v140, v11, 1, v0
	v_lshlrev_b32_e32 v0, 14, v12
	v_and_b32_e32 v0, 0xffff8000, v0
	v_lshl_add_u32 v0, v13, 11, v0
	v_and_b32_e32 v1, 1, v12
	s_waitcnt vmcnt(10)
	s_barrier
	s_waitcnt vmcnt(6)
	v_lshl_or_b32 v0, v1, 6, v0
	s_mov_b64 s[28:29], s[90:91]
	s_mov_b32 s67, s90
	v_lshl_add_u32 v142, v14, 1, v0
	s_add_i32 s89, 0, 0x10000
	s_add_i32 s90, 0, 0x14000
	s_movk_i32 s40, 0xe800
	v_mbcnt_lo_u32_b32 v0, -1, 0
	v_mov_b32_e32 v141, v137
	v_mov_b32_e32 v143, v137
	v_mov_b64_e32 v[144:145], 0xa00
	v_mov_b64_e32 v[146:147], 0x9ff
	s_movk_i32 s88, 0x141
	v_add_u32_e32 v159, s89, v158
	v_add_u32_e32 v160, 0, v4
	v_add_u32_e32 v161, s90, v158
	s_mov_b32 s41, -1
	v_mbcnt_hi_u32_b32 v162, -1, v0
	s_barrier
	s_branch .LBB0_175

.LBB0_334:
	s_and_b32 s6, s0, 3
	s_mov_b64 s[0:1], 0x80
	s_add_i32 m0, s43, 0x18000
	v_lshl_add_u64 v[6:7], v[6:7], 0, s[0:1]
	s_ashr_i32 s56, s90, 31
	s_lshl_b32 s7, s3, 13
	s_lshl_b32 s8, s6, 12
	global_load_lds_dwordx4 v[6:7], off
	v_lshl_add_u64 v[4:5], v[4:5], 0, s[0:1]
	s_add_i32 m0, s43, 0x1a000
	s_add_i32 s57, s43, 0x8000
	s_add_i32 s58, s43, 0xa000
	global_load_lds_dwordx4 v[4:5], off
	v_lshl_add_u64 v[2:3], v[2:3], 0, s[0:1]
	s_mov_b32 m0, s57
	s_add_u32 s4, s46, 0x10080
	global_load_lds_dwordx4 v[2:3], off
	v_lshl_add_u64 v[0:1], v[0:1], 0, s[0:1]
	s_mov_b32 m0, s58
	s_addc_u32 s5, s47, 0
	global_load_lds_dwordx4 v[0:1], off
	s_add_i32 m0, s43, 0x1c000
	v_lshl_add_u64 v[0:1], s[4:5], 0, v[132:133]
	global_load_lds_dwordx4 v[0:1], off
	v_lshl_add_u64 v[0:1], s[4:5], 0, v[128:129]
	s_add_i32 m0, s43, 0x1e000
	s_sext_i32_i8 s62, s2
	global_load_lds_dwordx4 v[0:1], off
	v_and_b32_e32 v0, 15, v9
	v_bfe_u32 v1, v9, 4, 2
	v_lshl_or_b32 v140, s3, 6, v0
	v_lshlrev_b32_e32 v2, 4, v1
	v_cmp_gt_u32_e64 s[2:3], 8, v0
	v_lshl_or_b32 v2, v0, 6, v2
	v_lshlrev_b32_e32 v3, 2, v9
	v_cndmask_b32_e64 v0, 32, 0, s[2:3]
	v_lshl_or_b32 v0, v1, 3, v0
	v_lshl_or_b32 v142, s6, 6, v0
	v_lshlrev_b32_e32 v0, 14, v13
	v_and_b32_e32 v0, 0xffff8000, v0
	v_lshl_add_u32 v0, v12, 11, v0
	v_and_b32_e32 v1, 1, v13
	v_lshl_or_b32 v0, v1, 6, v0
	v_lshl_add_u32 v136, v14, 1, v0
	v_lshlrev_b32_e32 v0, 14, v8
	v_and_b32_e32 v0, 0xffff8000, v0
	v_and_b32_e32 v3, 32, v3
	s_waitcnt vmcnt(10)
	s_barrier
	s_waitcnt vmcnt(6)
	v_lshl_add_u32 v0, v10, 11, v0
	v_and_b32_e32 v1, 1, v8
	v_bitop3_b32 v4, v2, s7, v3 bitop3:0xde
	v_bitop3_b32 v141, v2, s8, v3 bitop3:0xde
	v_lshl_or_b32 v0, v1, 6, v0
	s_add_i32 s60, 0, 0x10000
	s_add_i32 s61, 0, 0x14000
	s_mov_b32 s59, s90
	v_mov_b32_e32 v137, v133
	v_lshl_add_u32 v138, v11, 1, v0
	v_mov_b32_e32 v139, v133
	v_add_u32_e32 v143, s60, v141
	v_add_u32_e32 v144, 0, v4
	v_add_u32_e32 v145, s61, v141
	s_barrier

.LBB0_658:
	s_and_b32 s6, s0, 3
	s_mov_b64 s[0:1], 0x80
	s_add_i32 m0, s63, 0x18000
	v_lshl_add_u64 v[8:9], v[8:9], 0, s[0:1]
	s_ashr_i32 s80, s90, 31
	s_lshl_b32 s7, s3, 13
	s_lshl_b32 s8, s6, 12
	global_load_lds_dwordx4 v[8:9], off
	v_lshl_add_u64 v[6:7], v[6:7], 0, s[0:1]
	s_add_i32 m0, s63, 0x1a000
	s_add_i32 s81, s63, 0x8000
	s_add_i32 s82, s63, 0xa000
	global_load_lds_dwordx4 v[6:7], off
	v_lshl_add_u64 v[2:3], v[2:3], 0, s[0:1]
	s_mov_b32 m0, s81
	s_add_u32 s4, s56, 0x10080
	global_load_lds_dwordx4 v[2:3], off
	v_lshl_add_u64 v[2:3], v[4:5], 0, s[0:1]
	s_mov_b32 m0, s82
	s_addc_u32 s5, s57, 0
	global_load_lds_dwordx4 v[2:3], off
	s_add_i32 m0, s63, 0x1c000
	v_lshl_add_u64 v[2:3], s[4:5], 0, v[172:173]
	global_load_lds_dwordx4 v[2:3], off
	v_lshl_add_u64 v[2:3], s[4:5], 0, v[168:169]
	s_add_i32 m0, s63, 0x1e000
	s_sext_i32_i8 s17, s2
	global_load_lds_dwordx4 v[2:3], off
	v_lshrrev_b32_e32 v3, 1, v11
	v_and_b32_e32 v3, 24, v3
	v_and_b32_e32 v2, 15, v11
	v_lshlrev_b32_e32 v4, 1, v3
	v_lshl_or_b32 v195, s3, 6, v2
	v_lshl_or_b32 v4, v2, 6, v4
	v_cmp_gt_u32_e64 s[2:3], 8, v2
	v_lshlrev_b32_e32 v2, 14, v14
	v_and_b32_e32 v2, 0xffff8000, v2
	v_lshl_or_b32 v198, s6, 6, v3
	v_lshl_add_u32 v2, v13, 11, v2
	v_and_b32_e32 v3, 1, v14
	v_lshl_or_b32 v2, v3, 6, v2
	v_lshl_add_u32 v2, v15, 1, v2
	v_mov_b32_e32 v3, v0
	s_mov_b64 s[4:5], 0x40080
	v_lshl_add_u64 v[176:177], v[2:3], 0, s[4:5]
	v_lshlrev_b32_e32 v2, 14, v1
	v_and_b32_e32 v2, 0xffff8000, v2
	v_lshlrev_b32_e32 v5, 2, v11
	v_lshl_add_u32 v2, v10, 11, v2
	v_and_b32_e32 v1, 1, v1
	v_and_b32_e32 v5, 32, v5
	s_waitcnt vmcnt(10)
	s_barrier
	s_waitcnt vmcnt(6)
	v_lshl_or_b32 v1, v1, 6, v2
	v_writelane_b32 v242, s90, 1
	v_bitop3_b32 v6, v4, s7, v5 bitop3:0xde
	v_lshl_add_u32 v2, v12, 1, v1
	v_writelane_b32 v242, s91, 2
	s_mov_b32 s83, s90
	v_bitop3_b32 v196, v4, s8, v5 bitop3:0xde
	v_cndmask_b32_e64 v197, 32, 0, s[2:3]
	v_lshl_add_u64 v[178:179], v[2:3], 0, s[4:5]
	v_mov_b64_e32 v[180:181], 0x200
	v_mov_b64_e32 v[182:183], 0x1ff
	s_mov_b32 s84, 0x20000
	s_mov_b64 s[6:7], 0x30000
	s_mov_b32 s85, 0x30000
	s_mov_b64 s[8:9], 0x80000
	s_mov_b32 s89, 0x80000
	s_mov_b64 s[10:11], 0x90000
	s_mov_b32 s90, 0x90000
	s_mov_b64 s[12:13], 0xa0000
	s_mov_b32 s91, 0xa0000
	s_mov_b64 s[42:43], 0xb0000
	s_mov_b32 s92, 0xb0000
	v_add_u32_e32 v199, 0, v6
	s_add_i32 s93, 0, 0x14000
	s_barrier
	s_branch .LBB0_660

.LBB0_731:
	s_ashr_i32 s82, s90, 31
	s_ashr_i32 s83, s16, 31
	s_cmp_eq_u64 s[36:37], 0
	s_cselect_b64 s[46:47], -1, 0
	s_cmp_lg_u64 s[36:37], 0
	s_cselect_b64 s[48:49], -1, 0
	s_cmp_lg_u64 s[26:27], 0
	s_mov_b64 s[52:53], 0x80
	s_cselect_b64 s[50:51], -1, 0
	s_and_b32 s84, s2, 3
	s_add_i32 m0, s78, 0x18000
	v_lshl_add_u64 v[6:7], v[6:7], 0, s[52:53]
	s_lshl_b32 s2, s3, 13
	s_lshl_b32 s6, s84, 12
	global_load_lds_dwordx4 v[6:7], off
	v_lshl_add_u64 v[4:5], v[4:5], 0, s[52:53]
	s_add_i32 m0, s78, 0x1a000
	s_add_i32 s85, s78, 0x8000
	s_add_i32 s87, s78, 0xa000
	global_load_lds_dwordx4 v[4:5], off
	v_lshl_add_u64 v[2:3], v[2:3], 0, s[52:53]
	s_mov_b32 m0, s85
	s_add_u32 s4, s62, 0x10080
	global_load_lds_dwordx4 v[2:3], off
	v_lshl_add_u64 v[0:1], v[0:1], 0, s[52:53]
	s_mov_b32 m0, s87
	s_addc_u32 s5, s63, 0
	global_load_lds_dwordx4 v[0:1], off
	s_add_i32 m0, s78, 0x1c000
	v_lshl_add_u64 v[0:1], s[4:5], 0, v[198:199]
	global_load_lds_dwordx4 v[0:1], off
	v_lshl_add_u64 v[0:1], s[4:5], 0, v[202:203]
	s_add_i32 m0, s78, 0x1e000
	v_lshlrev_b32_e32 v4, 2, v8
	global_load_lds_dwordx4 v[0:1], off
	v_bfe_u32 v0, v8, 4, 2
	v_and_b32_e32 v1, 15, v8
	v_lshlrev_b32_e32 v3, 4, v0
	v_lshl_or_b32 v3, v1, 6, v3
	v_and_b32_e32 v4, 32, v4
	v_lshl_or_b32 v195, s3, 6, v1
	v_lshlrev_b32_e32 v2, 3, v0
	v_bitop3_b32 v5, v3, s2, v4 bitop3:0xde
	v_cmp_eq_u32_e64 s[2:3], 0, v0
	v_lshlrev_b32_e32 v0, 14, v9
	v_and_b32_e32 v0, 0xffff8000, v0
	v_cmp_gt_u32_e64 s[4:5], 8, v1
	v_lshl_add_u32 v0, v10, 11, v0
	v_and_b32_e32 v1, 1, v9
	v_lshl_or_b32 v0, v1, 6, v0
	v_lshl_add_u32 v204, v11, 1, v0
	v_lshlrev_b32_e32 v0, 14, v12
	v_and_b32_e32 v0, 0xffff8000, v0
	v_lshl_add_u32 v0, v13, 11, v0
	v_and_b32_e32 v1, 1, v12
	s_waitcnt vmcnt(10)
	s_barrier
	s_waitcnt vmcnt(6)
	v_lshl_or_b32 v0, v1, 6, v0
	s_mov_b64 s[96:97], s[90:91]
	s_mov_b32 s88, s90
	v_bitop3_b32 v218, v3, s6, v4 bitop3:0xde
	v_lshl_add_u32 v206, v14, 1, v0
	s_add_i32 s89, 0, 0x10000
	s_add_i32 s90, 0, 0x14000
	v_mbcnt_lo_u32_b32 v0, -1, 0
	v_lshl_or_b32 v219, s84, 6, v2
	v_cndmask_b32_e64 v220, 32, 0, s[4:5]
	v_mov_b32_e32 v205, v199
	v_mov_b32_e32 v207, v199
	v_mov_b64_e32 v[208:209], 0x200
	v_mov_b64_e32 v[210:211], 0x1ff
	v_add_u32_e32 v221, s89, v218
	v_add_u32_e32 v222, 0, v5
	v_add_u32_e32 v223, s90, v218
	v_mbcnt_hi_u32_b32 v224, -1, v0
	s_mov_b32 s91, 0
	s_barrier
	s_branch .LBB0_733

.LBB0_896:
	s_mov_b64 s[8:9], 0x80
	s_and_b32 s7, s4, 3
	s_add_i32 m0, s54, 0x18000
	v_lshl_add_u64 v[6:7], v[6:7], 0, s[8:9]
	s_ashr_i32 s59, s90, 31
	s_lshl_b32 s10, s3, 13
	s_lshl_b32 s12, s7, 12
	global_load_lds_dwordx4 v[6:7], off
	v_lshl_add_u64 v[4:5], v[4:5], 0, s[8:9]
	s_add_i32 m0, s54, 0x1a000
	s_add_i32 s60, s54, 0x8000
	s_add_i32 s61, s54, 0xa000
	global_load_lds_dwordx4 v[4:5], off
	v_lshl_add_u64 v[2:3], v[2:3], 0, s[8:9]
	s_mov_b32 m0, s60
	s_add_u32 s4, s50, 0x10080
	global_load_lds_dwordx4 v[2:3], off
	v_lshl_add_u64 v[0:1], v[0:1], 0, s[8:9]
	s_mov_b32 m0, s61
	s_addc_u32 s5, s51, 0
	global_load_lds_dwordx4 v[0:1], off
	s_add_i32 m0, s54, 0x1c000
	v_lshl_add_u64 v[0:1], s[4:5], 0, v[132:133]
	global_load_lds_dwordx4 v[0:1], off
	v_lshl_add_u64 v[0:1], s[4:5], 0, v[128:129]
	s_add_i32 m0, s54, 0x1e000
	v_bfe_u32 v2, v10, 4, 2
	global_load_lds_dwordx4 v[0:1], off
	v_and_b32_e32 v1, 15, v10
	s_sext_i32_i8 s66, s2
	v_lshl_or_b32 v161, s3, 6, v1
	v_lshlrev_b32_e32 v0, 4, v2
	v_cmp_gt_u32_e64 s[2:3], 8, v1
	v_lshl_or_b32 v3, v1, 6, v0
	v_lshlrev_b32_e32 v4, 2, v10
	v_cndmask_b32_e64 v1, 32, 0, s[2:3]
	v_lshl_or_b32 v1, v2, 3, v1
	v_lshl_or_b32 v167, s7, 6, v1
	v_mov_b32_e32 v1, v133
	v_lshl_add_u64 v[136:137], s[0:1], 0, v[0:1]
	v_lshlrev_b32_e32 v0, 14, v13
	v_and_b32_e32 v0, 0xffff8000, v0
	v_lshl_add_u32 v0, v12, 11, v0
	v_and_b32_e32 v1, 1, v13
	v_lshl_or_b32 v0, v1, 6, v0
	v_lshl_add_u32 v138, v14, 1, v0
	v_lshlrev_b32_e32 v0, 14, v8
	v_and_b32_e32 v0, 0xffff8000, v0
	v_lshl_add_u32 v0, v9, 11, v0
	v_and_b32_e32 v1, 1, v8
	v_and_b32_e32 v4, 32, v4
	s_waitcnt vmcnt(10)
	s_barrier
	s_waitcnt vmcnt(6)
	v_lshl_or_b32 v0, v1, 6, v0
	v_bitop3_b32 v5, v3, s10, v4 bitop3:0xde
	v_bitop3_b32 v163, v3, s12, v4 bitop3:0xde
	v_lshl_add_u32 v140, v11, 1, v0
	s_add_i32 s63, 0, 0x10000
	s_add_i32 s64, 0, 0x14000
	v_mbcnt_lo_u32_b32 v0, -1, 0
	s_mov_b32 s62, s90
	v_mov_b32_e32 v139, v133
	v_mov_b32_e32 v141, v133
	v_mov_b64_e32 v[142:143], 0x100
	v_mov_b64_e32 v[144:145], 0xff
	v_add_u32_e32 v169, s63, v163
	v_add_u32_e32 v171, 0, v5
	v_add_u32_e32 v172, s64, v163
	s_mov_b32 s10, 0x3a800000
	s_mov_b32 s12, 0x358637bd
	s_mov_b32 s65, 0x800000
	v_mbcnt_hi_u32_b32 v173, -1, v0
	s_barrier

.LBB0_988:
	s_ashr_i32 s59, s90, 31
	s_ashr_i32 s60, s16, 31
	s_cmp_lg_u64 s[26:27], 0
	s_mov_b64 s[36:37], 0x80
	s_cselect_b64 s[12:13], -1, 0
	s_and_b32 s61, s2, 3
	s_add_i32 m0, s55, 0x18000
	v_lshl_add_u64 v[6:7], v[6:7], 0, s[36:37]
	s_lshl_b32 s2, s3, 13
	s_lshl_b32 s6, s61, 12
	global_load_lds_dwordx4 v[6:7], off
	v_lshl_add_u64 v[4:5], v[4:5], 0, s[36:37]
	s_add_i32 m0, s55, 0x1a000
	s_add_i32 s62, s55, 0x8000
	s_add_i32 s63, s55, 0xa000
	global_load_lds_dwordx4 v[4:5], off
	v_lshl_add_u64 v[2:3], v[2:3], 0, s[36:37]
	s_mov_b32 m0, s62
	s_add_u32 s4, s50, 0x8080
	global_load_lds_dwordx4 v[2:3], off
	v_lshl_add_u64 v[0:1], v[0:1], 0, s[36:37]
	s_mov_b32 m0, s63
	s_addc_u32 s5, s51, 0
	global_load_lds_dwordx4 v[0:1], off
	s_add_i32 m0, s55, 0x1c000
	v_lshl_add_u64 v[0:1], s[4:5], 0, v[138:139]
	global_load_lds_dwordx4 v[0:1], off
	v_lshl_add_u64 v[0:1], s[4:5], 0, v[142:143]
	s_add_i32 m0, s55, 0x1e000
	v_lshlrev_b32_e32 v4, 2, v8
	global_load_lds_dwordx4 v[0:1], off
	v_bfe_u32 v0, v8, 4, 2
	v_and_b32_e32 v1, 15, v8
	v_lshlrev_b32_e32 v3, 4, v0
	v_lshl_or_b32 v3, v1, 6, v3
	v_and_b32_e32 v4, 32, v4
	v_lshl_or_b32 v160, s3, 6, v1
	v_lshlrev_b32_e32 v2, 3, v0
	v_bitop3_b32 v5, v3, s2, v4 bitop3:0xde
	v_cmp_eq_u32_e64 s[2:3], 0, v0
	v_lshlrev_b32_e32 v0, 13, v9
	v_and_b32_e32 v0, 0xffffc000, v0
	v_cmp_gt_u32_e64 s[4:5], 8, v1
	v_lshl_add_u32 v0, v10, 10, v0
	v_and_b32_e32 v1, 1, v9
	v_lshl_or_b32 v0, v1, 6, v0
	v_lshl_add_u32 v144, v11, 1, v0
	v_lshlrev_b32_e32 v0, 13, v12
	v_and_b32_e32 v0, 0xffffc000, v0
	v_lshl_add_u32 v0, v13, 10, v0
	v_and_b32_e32 v1, 1, v12
	s_waitcnt vmcnt(10)
	s_barrier
	s_waitcnt vmcnt(6)
	v_lshl_or_b32 v0, v1, 6, v0
	v_bitop3_b32 v161, v3, s6, v4 bitop3:0xde
	v_lshl_add_u32 v146, v14, 1, v0
	s_add_i32 s65, 0, 0x10000
	s_add_i32 s66, 0, 0x14000
	v_mbcnt_lo_u32_b32 v0, -1, 0
	s_mov_b32 s64, s90
	v_lshl_or_b32 v162, s61, 6, v2
	v_cndmask_b32_e64 v163, 32, 0, s[4:5]
	v_mov_b32_e32 v145, v139
	v_mov_b32_e32 v147, v139
	v_mov_b64_e32 v[148:149], 0x200
	v_mov_b64_e32 v[150:151], 0x1ff
	v_add_u32_e32 v164, s65, v161
	v_add_u32_e32 v165, 0, v5
	v_add_u32_e32 v166, s66, v161
	v_mbcnt_hi_u32_b32 v167, -1, v0
	s_mov_b32 s67, 0
	s_barrier
	s_branch .LBB0_990

.LBB0_1089:
	s_lshl_b32 s5, s6, 5
	s_mov_b64 s[6:7], 0x80
	s_and_b32 s10, s5, 0x60
	s_add_i32 m0, s47, 0x18000
	v_lshl_add_u64 v[6:7], v[6:7], 0, s[6:7]
	s_ashr_i32 s52, s90, 31
	s_lshl_b32 s8, s3, 13
	s_lshl_b32 s28, s10, 7
	global_load_lds_dwordx4 v[6:7], off
	v_lshl_add_u64 v[4:5], v[4:5], 0, s[6:7]
	s_add_i32 m0, s47, 0x1a000
	s_add_i32 s53, s47, 0x8000
	s_add_i32 s54, s47, 0xa000
	global_load_lds_dwordx4 v[4:5], off
	v_lshl_add_u64 v[2:3], v[2:3], 0, s[6:7]
	s_mov_b32 m0, s53
	s_add_u32 s12, s42, 0x40080
	global_load_lds_dwordx4 v[2:3], off
	v_lshl_add_u64 v[0:1], v[0:1], 0, s[6:7]
	s_mov_b32 m0, s54
	s_addc_u32 s13, s43, 0
	global_load_lds_dwordx4 v[0:1], off
	s_add_i32 m0, s47, 0x1c000
	v_lshl_add_u64 v[0:1], s[12:13], 0, v[132:133]
	global_load_lds_dwordx4 v[0:1], off
	v_lshl_add_u64 v[0:1], s[12:13], 0, v[128:129]
	s_add_i32 m0, s47, 0x1e000
	v_bfe_u32 v2, v9, 4, 2
	global_load_lds_dwordx4 v[0:1], off
	v_and_b32_e32 v1, 15, v9
	v_lshlrev_b32_e32 v0, 4, v2
	v_lshlrev_b32_e32 v3, 2, v9
	v_lshl_or_b32 v155, s3, 6, v1
	v_lshl_or_b32 v1, v1, 6, v0
	v_and_b32_e32 v3, 32, v3
	v_bitop3_b32 v4, v1, s8, v3 bitop3:0xde
	v_bitop3_b32 v159, v1, s28, v3 bitop3:0xde
	v_mov_b32_e32 v1, v133
	v_lshl_add_u64 v[136:137], s[0:1], 0, v[0:1]
	v_lshlrev_b32_e32 v0, 14, v13
	v_and_b32_e32 v0, 0xffff8000, v0
	v_lshl_add_u32 v0, v12, 11, v0
	v_and_b32_e32 v1, 1, v13
	v_lshl_or_b32 v0, v1, 6, v0
	v_lshl_add_u32 v138, v14, 1, v0
	v_lshlrev_b32_e32 v0, 14, v8
	v_and_b32_e32 v0, 0xffff8000, v0
	v_lshl_add_u32 v0, v10, 11, v0
	v_and_b32_e32 v1, 1, v8
	s_waitcnt vmcnt(10)
	s_barrier
	s_waitcnt vmcnt(6)
	v_lshl_or_b32 v0, v1, 6, v0
	v_lshl_add_u32 v140, v11, 1, v0
	s_add_i32 s56, 0, 0x10000
	s_add_i32 s57, 0, 0x14000
	v_mbcnt_lo_u32_b32 v0, -1, 0
	s_sext_i32_i8 s5, s2
	s_mov_b32 s55, s90
	v_lshl_or_b32 v163, v2, 3, s10
	v_mov_b32_e32 v139, v133
	v_mov_b32_e32 v141, v133
	v_mov_b64_e32 v[142:143], 0xb00
	v_mov_b64_e32 v[144:145], 0xaff
	v_add_u32_e32 v167, s56, v159
	v_add_u32_e32 v171, 0, v4
	v_add_u32_e32 v175, s57, v159
	v_mbcnt_hi_u32_b32 v177, -1, v0
	s_mov_b32 s8, 0x3a800000
	s_mov_b32 s10, 0x358637bd
	s_mov_b32 s58, 0x800000
	s_movk_i32 s59, 0x1600
	s_barrier

.LBB0_1156:
	s_ashr_i32 s51, s90, 31
	s_ashr_i32 s52, s16, 31
	s_cmp_lg_u64 s[24:25], 0
	s_mov_b64 s[36:37], 0x80
	s_cselect_b64 s[12:13], -1, 0
	s_and_b32 s53, s1, 3
	s_add_i32 m0, s47, 0x18000
	v_lshl_add_u64 v[6:7], v[6:7], 0, s[36:37]
	s_lshl_b32 s1, s2, 13
	s_lshl_b32 s3, s53, 12
	global_load_lds_dwordx4 v[6:7], off
	v_lshl_add_u64 v[4:5], v[4:5], 0, s[36:37]
	s_add_i32 m0, s47, 0x1a000
	s_add_i32 s54, s47, 0x8000
	s_add_i32 s55, s47, 0xa000
	global_load_lds_dwordx4 v[4:5], off
	v_lshl_add_u64 v[2:3], v[2:3], 0, s[36:37]
	s_mov_b32 m0, s54
	s_add_u32 s4, s42, 0x2c080
	global_load_lds_dwordx4 v[2:3], off
	v_lshl_add_u64 v[0:1], v[0:1], 0, s[36:37]
	s_mov_b32 m0, s55
	s_addc_u32 s5, s43, 0
	global_load_lds_dwordx4 v[0:1], off
	s_add_i32 m0, s47, 0x1c000
	v_lshl_add_u64 v[0:1], s[4:5], 0, v[142:143]
	global_load_lds_dwordx4 v[0:1], off
	v_lshl_add_u64 v[0:1], s[4:5], 0, v[146:147]
	s_add_i32 m0, s47, 0x1e000
	s_add_i32 s57, 0, 0x10000
	global_load_lds_dwordx4 v[0:1], off
	v_bfe_u32 v0, v194, 4, 2
	v_and_b32_e32 v1, 15, v194
	v_lshlrev_b32_e32 v3, 4, v0
	v_lshl_or_b32 v164, s2, 6, v1
	v_lshl_or_b32 v1, v1, 6, v3
	v_lshlrev_b32_e32 v3, 2, v194
	v_and_b32_e32 v3, 32, v3
	v_lshlrev_b32_e32 v2, 3, v0
	v_bitop3_b32 v4, v1, s1, v3 bitop3:0xde
	v_bitop3_b32 v165, v1, s3, v3 bitop3:0xde
	v_cmp_eq_u32_e64 s[2:3], 0, v0
	v_lshrrev_b32_e32 v1, 1, v8
	v_mul_lo_u32 v0, v10, s0
	s_mov_b32 s1, 0xb000
	v_mad_u64_u32 v[0:1], s[4:5], v1, s1, v[0:1]
	v_or_b32_e32 v0, v0, v9
	v_add_lshl_u32 v0, v0, v11, 1
	v_mov_b32_e32 v1, v143
	s_mov_b64 s[4:5], 0xb0080
	v_lshl_add_u64 v[148:149], v[0:1], 0, s[4:5]
	v_lshrrev_b32_e32 v1, 1, v12
	v_mul_lo_u32 v0, v13, s0
	v_mad_u64_u32 v[0:1], s[0:1], v1, s1, v[0:1]
	v_or_b32_e32 v0, v0, v14
	s_waitcnt vmcnt(10)
	s_barrier
	s_waitcnt vmcnt(6)
	v_add_lshl_u32 v0, v0, v15, 1
	v_mov_b32_e32 v1, v143
	v_lshl_add_u64 v[150:151], v[0:1], 0, s[4:5]
	s_add_i32 s58, 0, 0x14000
	v_mbcnt_lo_u32_b32 v0, -1, 0
	s_mov_b32 s56, s90
	v_lshl_or_b32 v166, s53, 6, v2
	v_mov_b64_e32 v[152:153], 0x200
	v_mov_b64_e32 v[154:155], 0x1ff
	v_add_u32_e32 v167, s57, v165
	v_add_u32_e32 v168, 0, v4
	v_add_u32_e32 v169, s58, v165
	v_mbcnt_hi_u32_b32 v170, -1, v0
	s_mov_b32 s59, 0
	s_barrier
	s_branch .LBB0_1158
